# local barrier waiters wait for XGEN > generation (robust if the previous full barrier's XGEN bump has not landed yet)
# baseline (speedup 1.0000x reference)
.Lxg_1:
	flat_load_dword v234, v[2:3] sc1
	s_waitcnt vmcnt(0) lgkmcnt(0)
	v_cmp_gt_u32_e32 vcc, v234, v1
	s_cbranch_vccz .Lxg_1
	buffer_inv sc1
	s_waitcnt vmcnt(0)
	s_branch .LBB0_404

.Lxg_6:
	flat_load_dword v234, v[2:3] sc1
	s_waitcnt vmcnt(0) lgkmcnt(0)
	v_cmp_gt_u32_e32 vcc, v234, v1
	s_cbranch_vccz .Lxg_6
	s_waitcnt vmcnt(0)
	s_branch .LBB0_1345
